# F1 merge GEMM: gate loads issued at the last prefetching K-iteration (youngest VMEM ops), counted waits skip them
# speedup vs baseline: 1.0116x; 1.0116x over previous
.LBB0_162:
	s_cmp_eq_u32 s11, 1
	s_mov_b32 s3, 0x530000
	s_cselect_b32 s0, s88, s82
	s_cselect_b32 s2, s89, s83
	s_cselect_b32 s4, s3, 0x630000
	s_cselect_b32 s12, 16, 8
	s_cselect_b32 s13, 10, 9
	s_cmp_eq_u32 s11, 0
	s_cselect_b32 s3, s81, s2
	s_cselect_b32 s2, s80, s0
	s_cselect_b32 s0, 0x4b0000, s4
	s_lshl_b32 s0, s0, 1
	v_mov_b32_e32 v4, v204
	s_add_u32 s4, s97, s0
	v_readfirstlane_b32 s14, v4
	s_addc_u32 s5, s79, 0
	s_ashr_i32 s15, s14, 6
	v_bfe_u32 v0, v4, 3, 3
	s_and_b32 s16, s15, 1
	v_lshl_or_b32 v5, s15, 3, v0
	v_and_b32_e32 v0, 7, v4
	s_lshl_b32 s0, s16, 2
	v_bfe_u32 v6, v4, 4, 2
	v_bitop3_b32 v7, s0, v0, v6 bitop3:0x36
	v_add_u32_e32 v0, s9, v5
	v_ashrrev_i32_e32 v1, 31, v0
	v_lshlrev_b64 v[2:3], s13, v[0:1]
	v_lshl_add_u64 v[2:3], v[2:3], 1, s[2:3]
	v_lshlrev_b32_e32 v188, 4, v7
	v_lshl_add_u64 v[178:179], v[2:3], 0, v[188:189]
	v_add_u32_e32 v2, 64, v0
	v_ashrrev_i32_e32 v3, 31, v2
	v_lshlrev_b64 v[2:3], s13, v[2:3]
	v_lshl_add_u64 v[2:3], v[2:3], 1, s[2:3]
	v_lshl_add_u64 v[180:181], v[2:3], 0, v[188:189]
	v_add_u32_e32 v2, 0x80, v0
	v_add_u32_e32 v0, 0xc0, v0
	v_ashrrev_i32_e32 v1, 31, v0
	v_lshlrev_b64 v[0:1], s13, v[0:1]
	v_ashrrev_i32_e32 v3, 31, v2
	v_lshl_add_u64 v[0:1], v[0:1], 1, s[2:3]
	v_lshlrev_b64 v[2:3], s13, v[2:3]
	v_lshl_add_u64 v[184:185], v[0:1], 0, v[188:189]
	v_add_u32_e32 v0, s10, v5
	v_lshl_add_u64 v[2:3], v[2:3], 1, s[2:3]
	v_ashrrev_i32_e32 v1, 31, v0
	v_lshl_add_u64 v[182:183], v[2:3], 0, v[188:189]
	v_lshlrev_b64 v[2:3], s13, v[0:1]
	v_add_u32_e32 v0, 64, v0
	v_ashrrev_i32_e32 v1, 31, v0
	s_lshl_b32 s2, s15, 10
	v_lshlrev_b64 v[0:1], s13, v[0:1]
	s_add_i32 s13, s2, 0
	s_mov_b32 m0, s13
	v_lshl_add_u64 v[2:3], v[2:3], 1, s[4:5]
	global_load_lds_dwordx4 v[178:179], off
	s_add_i32 m0, s13, 0x2000
	v_lshl_add_u64 v[186:187], v[2:3], 0, v[188:189]
	global_load_lds_dwordx4 v[180:181], off
	s_add_i32 m0, s13, 0x4000
	v_lshl_add_u64 v[0:1], v[0:1], 1, s[4:5]
	global_load_lds_dwordx4 v[182:183], off
	s_add_i32 m0, s13, 0x6000
	v_lshl_add_u64 v[190:191], v[0:1], 0, v[188:189]
	global_load_lds_dwordx4 v[184:185], off
	s_add_i32 m0, s13, 0x8000
	v_lshl_add_u64 v[0:1], v[178:179], 0, s[92:93]
	global_load_lds_dwordx4 v[186:187], off
	s_add_i32 m0, s13, 0xa000
	s_lshr_b32 s2, s14, 1
	global_load_lds_dwordx4 v[190:191], off
	s_add_i32 m0, s13, 0xc000
	s_and_b32 s2, s2, 0x1ffffc0
	global_load_lds_dwordx4 v[0:1], off
	v_lshl_add_u64 v[0:1], v[180:181], 0, s[92:93]
	s_add_i32 m0, s13, 0xe000
	s_movk_i32 s0, 0x80
	global_load_lds_dwordx4 v[0:1], off
	v_lshl_add_u64 v[0:1], v[182:183], 0, s[92:93]
	s_add_i32 m0, s13, 0x10000
	s_lshl_b32 s14, s16, 13
	global_load_lds_dwordx4 v[0:1], off
	v_lshl_add_u64 v[0:1], v[184:185], 0, s[92:93]
	s_add_i32 m0, s13, 0x12000
	s_mov_b32 s15, 0
	global_load_lds_dwordx4 v[0:1], off
	v_lshl_add_u64 v[0:1], v[186:187], 0, s[92:93]
	s_add_i32 m0, s13, 0x14000
	s_mov_b32 s16, 0
	global_load_lds_dwordx4 v[0:1], off
	v_lshl_add_u64 v[0:1], v[190:191], 0, s[92:93]
	s_add_i32 m0, s13, 0x16000
	v_mov_b32_e32 v2, v192
	global_load_lds_dwordx4 v[0:1], off
	s_waitcnt vmcnt(6)
	v_bfe_u32 v1, v4, 1, 3
	s_waitcnt lgkmcnt(0)
	s_barrier
	v_and_b32_e32 v0, 15, v4
	v_xor_b32_e32 v1, v6, v1
	v_lshlrev_b32_e32 v188, 4, v1
	v_or_b32_e32 v1, s2, v0
	v_lshlrev_b32_e32 v193, 7, v1
	v_lshlrev_b32_e32 v194, 7, v0
	v_xor_b32_e32 v195, 64, v188
	v_mov_b32_e32 v0, 0
	v_mov_b32_e32 v1, v192
	v_mov_b32_e32 v3, v192
	v_mov_b32_e32 v4, 0
	v_mov_b32_e32 v5, v192
	v_mov_b32_e32 v6, v192
	v_mov_b32_e32 v7, v192
	v_mov_b32_e32 v8, 0
	v_mov_b32_e32 v9, v192
	v_mov_b32_e32 v10, v192
	v_mov_b32_e32 v11, v192
	v_mov_b32_e32 v12, 0
	v_mov_b32_e32 v13, v192
	v_mov_b32_e32 v14, v192
	v_mov_b32_e32 v15, v192
	v_mov_b32_e32 v16, 0
	v_mov_b32_e32 v17, v192
	v_mov_b32_e32 v18, v192
	v_mov_b32_e32 v19, v192
	v_mov_b32_e32 v20, 0
	v_mov_b32_e32 v21, v192
	v_mov_b32_e32 v22, v192
	v_mov_b32_e32 v23, v192
	v_mov_b32_e32 v24, 0
	v_mov_b32_e32 v25, v192
	v_mov_b32_e32 v26, v192
	v_mov_b32_e32 v27, v192
	v_mov_b32_e32 v28, 0
	v_mov_b32_e32 v29, v192
	v_mov_b32_e32 v30, v192
	v_mov_b32_e32 v31, v192
	v_mov_b32_e32 v32, 0
	v_mov_b32_e32 v33, v192
	v_mov_b32_e32 v34, v192
	v_mov_b32_e32 v35, v192
	v_mov_b32_e32 v36, 0
	v_mov_b32_e32 v37, v192
	v_mov_b32_e32 v38, v192
	v_mov_b32_e32 v39, v192
	v_mov_b32_e32 v40, 0
	v_mov_b32_e32 v41, v192
	v_mov_b32_e32 v42, v192
	v_mov_b32_e32 v43, v192
	v_mov_b32_e32 v44, 0
	v_mov_b32_e32 v45, v192
	v_mov_b32_e32 v46, v192
	v_mov_b32_e32 v47, v192
	v_mov_b32_e32 v48, 0
	v_mov_b32_e32 v49, v192
	v_mov_b32_e32 v50, v192
	v_mov_b32_e32 v51, v192
	v_mov_b32_e32 v52, 0
	v_mov_b32_e32 v53, v192
	v_mov_b32_e32 v54, v192
	v_mov_b32_e32 v55, v192
	v_mov_b32_e32 v56, 0
	v_mov_b32_e32 v57, v192
	v_mov_b32_e32 v58, v192
	v_mov_b32_e32 v59, v192
	v_mov_b32_e32 v60, 0
	v_mov_b32_e32 v61, v192
	v_mov_b32_e32 v62, v192
	v_mov_b32_e32 v63, v192
	s_branch .LBB0_164

.LBB0_166:
	s_andn2_b64 vcc, exec, s[4:5]
	s_cbranch_vccnz .LBB0_168
	s_add_i32 s4, s18, 0xffff4000
	s_cmp_lg_u32 s15, 0
	s_cselect_b32 s17, s4, 0x18000
	s_lshl_b64 s[4:5], s[0:1], 1
	s_add_i32 s17, s13, s17
	v_lshl_add_u64 v[196:197], v[178:179], 0, s[4:5]
	s_mov_b32 m0, s17
	s_nop 0
	global_load_lds_dwordx4 v[196:197], off
	v_lshl_add_u64 v[196:197], v[180:181], 0, s[4:5]
	s_add_i32 m0, s17, 0x2000
	s_nop 0
	global_load_lds_dwordx4 v[196:197], off
	v_lshl_add_u64 v[196:197], v[182:183], 0, s[4:5]
	s_add_i32 m0, s17, 0x4000
	s_nop 0
	global_load_lds_dwordx4 v[196:197], off
	v_lshl_add_u64 v[196:197], v[184:185], 0, s[4:5]
	s_add_i32 m0, s17, 0x6000
	s_nop 0
	global_load_lds_dwordx4 v[196:197], off
	v_lshl_add_u64 v[196:197], v[186:187], 0, s[4:5]
	s_add_i32 m0, s17, 0x8000
	s_nop 0
	global_load_lds_dwordx4 v[196:197], off
	v_lshl_add_u64 v[196:197], v[190:191], 0, s[4:5]
	s_add_i32 m0, s17, 0xa000
	s_mov_b32 s17, s18
	global_load_lds_dwordx4 v[196:197], off
	s_add_i32 vcc_lo, s16, 3
	s_cmp_lg_u32 vcc_lo, s12
	s_cbranch_scc1 .Lf1g_skip
	s_lshl_b32 vcc_lo, s11, 11
	s_add_u32 vcc_lo, s94, vcc_lo
	s_addc_u32 vcc_hi, s95, 0
	v_lshl_add_u64 v[196:197], vcc, 0, v[94:95]
	v_lshl_add_u64 v[196:197], v[196:197], 0, v[66:67]
	global_load_dwordx2 v[176:177], v[196:197], off
	global_load_dwordx2 v[174:175], v[196:197], off offset:32
	global_load_dwordx2 v[172:173], v[196:197], off offset:64
	global_load_dwordx2 v[170:171], v[196:197], off offset:96
	v_lshl_add_u64 v[196:197], vcc, 0, v[114:115]
	v_lshl_add_u64 v[196:197], v[196:197], 0, v[66:67]
	global_load_dwordx2 v[168:169], v[196:197], off
	global_load_dwordx2 v[166:167], v[196:197], off offset:32
	global_load_dwordx2 v[164:165], v[196:197], off offset:64
	global_load_dwordx2 v[162:163], v[196:197], off offset:96
	v_lshl_add_u64 v[196:197], vcc, 0, v[126:127]
	v_lshl_add_u64 v[196:197], v[196:197], 0, v[66:67]
	global_load_dwordx2 v[160:161], v[196:197], off
	global_load_dwordx2 v[158:159], v[196:197], off offset:32
	global_load_dwordx2 v[156:157], v[196:197], off offset:64
	global_load_dwordx2 v[154:155], v[196:197], off offset:96
	v_lshl_add_u64 v[196:197], vcc, 0, v[128:129]
	v_lshl_add_u64 v[196:197], v[196:197], 0, v[66:67]
	global_load_dwordx2 v[152:153], v[196:197], off
	global_load_dwordx2 v[150:151], v[196:197], off offset:32
	global_load_dwordx2 v[148:149], v[196:197], off offset:64
	global_load_dwordx2 v[146:147], v[196:197], off offset:96
.Lf1g_skip:
.LBB0_168:
	s_add_i32 s4, s17, 0
	s_add_i32 s5, s4, s14
	v_add_u32_e32 v206, s5, v194
	v_add_u32_e32 v215, v206, v188
	v_add_u32_e32 v228, s4, v193
	v_add_u32_e32 v229, v228, v188
	ds_read_b128 v[200:203], v229
	ds_read_b128 v[196:199], v215 offset:32768
	ds_read_b128 v[216:219], v215 offset:34816
	ds_read_b128 v[220:223], v215 offset:36864
	ds_read_b128 v[224:227], v215 offset:38912
	ds_read_b128 v[246:249], v229 offset:2048
	v_add_u32_e32 v206, v206, v195
	v_add_u32_e32 v228, v228, v195
	s_waitcnt lgkmcnt(4)
	v_mfma_f32_16x16x32_bf16 v[60:63], v[196:199], v[200:203], v[60:63]
	s_waitcnt lgkmcnt(3)
	v_mfma_f32_16x16x32_bf16 v[56:59], v[216:219], v[200:203], v[56:59]
	s_waitcnt lgkmcnt(2)
	v_mfma_f32_16x16x32_bf16 v[52:55], v[220:223], v[200:203], v[52:55]
	s_waitcnt lgkmcnt(1)
	v_mfma_f32_16x16x32_bf16 v[48:51], v[224:227], v[200:203], v[48:51]
	ds_read_b128 v[200:203], v229 offset:4096
	ds_read_b128 v[230:233], v206 offset:32768
	ds_read_b128 v[234:237], v206 offset:34816
	s_waitcnt lgkmcnt(3)
	v_mfma_f32_16x16x32_bf16 v[44:47], v[196:199], v[246:249], v[44:47]
	v_mfma_f32_16x16x32_bf16 v[40:43], v[216:219], v[246:249], v[40:43]
	v_mfma_f32_16x16x32_bf16 v[36:39], v[220:223], v[246:249], v[36:39]
	v_mfma_f32_16x16x32_bf16 v[32:35], v[224:227], v[246:249], v[32:35]
	ds_read_b128 v[246:249], v229 offset:6144
	ds_read_b128 v[238:241], v206 offset:36864
	ds_read_b128 v[242:245], v206 offset:38912
	s_waitcnt lgkmcnt(5)
	v_mfma_f32_16x16x32_bf16 v[28:31], v[196:199], v[200:203], v[28:31]
	v_mfma_f32_16x16x32_bf16 v[24:27], v[216:219], v[200:203], v[24:27]
	v_mfma_f32_16x16x32_bf16 v[20:23], v[220:223], v[200:203], v[20:23]
	v_mfma_f32_16x16x32_bf16 v[16:19], v[224:227], v[200:203], v[16:19]
	ds_read_b128 v[200:203], v228
	s_waitcnt lgkmcnt(3)
	v_mfma_f32_16x16x32_bf16 v[12:15], v[196:199], v[246:249], v[12:15]
	v_mfma_f32_16x16x32_bf16 v[8:11], v[216:219], v[246:249], v[8:11]
	v_mfma_f32_16x16x32_bf16 v[4:7], v[220:223], v[246:249], v[4:7]
	v_mfma_f32_16x16x32_bf16 v[0:3], v[224:227], v[246:249], v[0:3]
	ds_read_b128 v[246:249], v228 offset:2048
	s_waitcnt lgkmcnt(1)
	v_mfma_f32_16x16x32_bf16 v[60:63], v[230:233], v[200:203], v[60:63]
	v_mfma_f32_16x16x32_bf16 v[56:59], v[234:237], v[200:203], v[56:59]
	v_mfma_f32_16x16x32_bf16 v[52:55], v[238:241], v[200:203], v[52:55]
	v_mfma_f32_16x16x32_bf16 v[48:51], v[242:245], v[200:203], v[48:51]
	ds_read_b128 v[200:203], v228 offset:4096
	s_waitcnt lgkmcnt(1)
	v_mfma_f32_16x16x32_bf16 v[44:47], v[230:233], v[246:249], v[44:47]
	v_mfma_f32_16x16x32_bf16 v[40:43], v[234:237], v[246:249], v[40:43]
	v_mfma_f32_16x16x32_bf16 v[36:39], v[238:241], v[246:249], v[36:39]
	v_mfma_f32_16x16x32_bf16 v[32:35], v[242:245], v[246:249], v[32:35]
	ds_read_b128 v[246:249], v228 offset:6144
	s_waitcnt lgkmcnt(1)
	v_mfma_f32_16x16x32_bf16 v[28:31], v[230:233], v[200:203], v[28:31]
	v_mfma_f32_16x16x32_bf16 v[24:27], v[234:237], v[200:203], v[24:27]
	v_mfma_f32_16x16x32_bf16 v[20:23], v[238:241], v[200:203], v[20:23]
	v_mfma_f32_16x16x32_bf16 v[16:19], v[242:245], v[200:203], v[16:19]
	s_waitcnt lgkmcnt(0)
	v_mfma_f32_16x16x32_bf16 v[12:15], v[230:233], v[246:249], v[12:15]
	v_mfma_f32_16x16x32_bf16 v[8:11], v[234:237], v[246:249], v[8:11]
	v_mfma_f32_16x16x32_bf16 v[4:7], v[238:241], v[246:249], v[4:7]
	v_mfma_f32_16x16x32_bf16 v[0:3], v[242:245], v[246:249], v[0:3]
	s_mov_b64 s[4:5], -1
	s_and_b64 vcc, exec, s[2:3]
	s_cbranch_vccz .LBB0_170
	s_waitcnt vmcnt(16)
	s_waitcnt lgkmcnt(0)
	s_barrier
	s_mov_b64 s[4:5], 0
.LBB0_170:
	s_andn2_b64 vcc, exec, s[4:5]
	s_cbranch_vccnz .LBB0_163
	s_add_i32 vcc_lo, s16, 3
	s_cmp_lg_u32 vcc_lo, s12
	s_cbranch_scc1 .Lf1g_w6
	s_waitcnt vmcnt(22)
	s_branch .Lf1g_wd
.Lf1g_w6:
	s_waitcnt vmcnt(6)
.Lf1g_wd:
	s_waitcnt lgkmcnt(0)
	s_barrier
	s_branch .LBB0_163
